# hgrn pass1: next-chunk loads issued after barrier1 (saddr form, dedicated landing regs), pack at loop top; plus all previous
# speedup vs baseline: 1.0456x; 1.0047x over previous
.LBB0_383:
	s_and_b32 s0, s8, 7
	s_cmp_eq_u32 s0, 7
	v_readfirstlane_b32 s1, v44
	s_cbranch_scc1 .LBB0_382
	s_and_b32 s3, s2, 7
	s_lshl_b32 s9, s3, 10
	s_ashr_i32 s3, s1, 6
	s_ashr_i32 s4, s8, 7
	s_bfe_u32 s1, s8, 0x10003
	s_xor_b32 s10, s9, 0x1f80
	s_ashr_i32 s5, s4, 31
	s_lshl_b32 s18, s1, 25
	v_readlane_b32 s19, v250, 42
	s_add_u32 s18, s19, s18
	v_readlane_b32 s19, v250, 43
	s_addc_u32 s19, s19, 0
	s_lshl_b64 s[4:5], s[4:5], 24
	s_add_u32 s18, s18, s4
	s_addc_u32 s19, s19, s5
	v_readlane_b32 s20, v250, 44
	s_add_u32 s4, s20, s4
	v_readlane_b32 s20, v250, 45
	s_addc_u32 s5, s20, s5
	s_lshl_b32 s20, s8, 4
	s_and_b32 s20, s20, 0x700
	s_add_u32 s18, s18, s20
	s_addc_u32 s19, s19, 0
	s_add_u32 s20, s4, s20
	s_addc_u32 s21, s5, 0
	s_lshl_b32 s4, s0, 10
	s_xor_b32 s5, s4, 0x1fc0
	s_cmp_eq_u32 s1, 0
	s_cselect_b64 s[44:45], -1, 0
	v_cndmask_b32_e64 v0, v82, v81, s[44:45]
	s_and_b64 s[0:1], s[44:45], exec
	v_lshl_or_b32 v46, v0, 11, v80
	s_cselect_b32 s24, 0x800, s78
	v_add_u32_e32 v48, s24, v46
	v_add_u32_e32 v50, s24, v48
	v_add_u32_e32 v52, s24, v50
	v_add_u32_e32 v54, s24, v52
	s_cselect_b32 s0, s4, s5
	v_add_u32_e32 v56, s24, v54
	s_lshl_b32 s4, s0, 11
	v_add_u32_e32 v58, s24, v56
	s_add_u32 s0, s18, s4
	v_add_u32_e32 v60, s24, v58
	s_addc_u32 s1, s19, 0
	v_add_u32_e32 v62, s24, v60
	s_add_u32 s4, s20, s4
	v_add_u32_e32 v66, s24, v62
	s_addc_u32 s5, s21, 0
	v_add_u32_e32 v68, s24, v66
	global_load_ushort v212, v46, s[4:5]
	global_load_ushort v213, v48, s[4:5]
	global_load_ushort v214, v50, s[4:5]
	global_load_ushort v215, v52, s[4:5]
	global_load_ushort v216, v54, s[4:5]
	global_load_ushort v217, v56, s[4:5]
	global_load_ushort v218, v58, s[4:5]
	global_load_ushort v219, v60, s[4:5]
	v_add_u32_e32 v70, s24, v68
	global_load_ushort v220, v62, s[4:5]
	global_load_ushort v221, v66, s[4:5]
	global_load_ushort v222, v68, s[4:5]
	global_load_ushort v223, v70, s[4:5]
	v_add_u32_e32 v72, s24, v70
	v_add_u32_e32 v74, s24, v72
	v_add_u32_e32 v76, s24, v74
	v_add_u32_e32 v78, s24, v76
	global_load_ushort v224, v72, s[4:5]
	global_load_ushort v225, v74, s[4:5]
	global_load_ushort v226, v76, s[4:5]
	global_load_ushort v227, v78, s[4:5]
	global_load_ushort v228, v46, s[0:1]
	global_load_ushort v229, v48, s[0:1]
	global_load_ushort v230, v50, s[0:1]
	global_load_ushort v231, v52, s[0:1]
	global_load_ushort v232, v54, s[0:1]
	global_load_ushort v233, v56, s[0:1]
	global_load_ushort v234, v58, s[0:1]
	global_load_ushort v235, v60, s[0:1]
	global_load_ushort v236, v62, s[0:1]
	global_load_ushort v237, v66, s[0:1]
	global_load_ushort v238, v68, s[0:1]
	global_load_ushort v239, v70, s[0:1]
	global_load_ushort v240, v72, s[0:1]
	global_load_ushort v241, v74, s[0:1]
	global_load_ushort v242, v76, s[0:1]
	global_load_ushort v243, v78, s[0:1]
	v_lshl_or_b32 v20, s3, 4, v65
	v_mov_b32_e32 v91, 0
	v_mul_lo_u32 v20, v20, s25
	v_mov_b32_e32 v47, v64
	v_mov_b32_e32 v49, v64
	v_mov_b32_e32 v51, v64
	v_mov_b32_e32 v53, v64
	v_mov_b32_e32 v55, v64
	v_mov_b32_e32 v57, v64
	v_mov_b32_e32 v59, v64
	v_mov_b32_e32 v61, v64
	v_mov_b32_e32 v63, v64
	v_mov_b32_e32 v67, v64
	v_mov_b32_e32 v69, v64
	v_mov_b32_e32 v71, v64
	v_mov_b32_e32 v73, v64
	v_mov_b32_e32 v75, v64
	v_mov_b32_e32 v77, v64
	v_mov_b32_e32 v79, v64
	s_mov_b32 s24, 64
	v_mov_b32_e32 v0, 0
	v_mov_b32_e32 v1, v91
	v_mov_b32_e32 v2, v91
	v_mov_b32_e32 v3, v91
	v_add_u32_e32 v43, v87, v20
	v_mov_b32_e32 v20, 0
	v_mov_b32_e32 v21, v91
	v_mov_b32_e32 v22, v91
	v_mov_b32_e32 v23, v91
	v_mov_b32_e32 v24, 0
	v_mov_b32_e32 v25, v91
	v_mov_b32_e32 v26, v91
	v_mov_b32_e32 v27, v91
	v_mov_b32_e32 v28, 0
	v_mov_b32_e32 v29, v91
	v_mov_b32_e32 v30, v91
	v_mov_b32_e32 v31, v91
	v_mov_b32_e32 v16, 0
	v_mov_b32_e32 v17, v91
	v_mov_b32_e32 v18, v91
	v_mov_b32_e32 v19, v91
	v_mov_b32_e32 v4, 0
	v_mov_b32_e32 v5, v91
	v_mov_b32_e32 v6, v91
	v_mov_b32_e32 v7, v91
	v_mov_b32_e32 v8, 0
	v_mov_b32_e32 v9, v91
	v_mov_b32_e32 v10, v91
	v_mov_b32_e32 v11, v91
	v_mov_b32_e32 v12, 0
	v_mov_b32_e32 v13, v91
	v_mov_b32_e32 v14, v91
	v_mov_b32_e32 v15, v91
	s_waitcnt vmcnt(0)
	s_branch .LBB0_386
.LBB0_385:
	s_or_b64 exec, exec, s[0:1]
	v_mul_f32_e32 v39, 0x3fb8aa3b, v93
	v_exp_f32_e32 v39, v39
	v_mul_f32_e32 v92, 0x3fb8aa3b, v92
	v_exp_f32_e32 v92, v92
	v_sub_f32_e32 v39, 1.0, v39
	v_sub_f32_e32 v92, 1.0, v92
	v_mul_f32_e32 v39, v39, v94
	v_mul_f32_e32 v92, v92, v96
	v_cvt_pk_bf16_f32 v39, v92, v39
	ds_write_b128 v90, v[32:35] offset:60928
	ds_write_b128 v90, v[36:39] offset:60944
	s_waitcnt lgkmcnt(0)
	s_barrier
	v_add_u32_e32 v92, 0, v86
	v_add_u32_e32 v92, 0x1aa00, v92
	ds_read_b128 v[110:113], v43
	ds_read_b128 v[114:117], v43 offset:64
	ds_read_b128 v[118:121], v92
	ds_read_b128 v[122:125], v88 offset:60928
	ds_read_b128 v[126:129], v88 offset:60992
	ds_read_b128 v[130:133], v92 offset:64
	ds_read_b128 v[134:137], v88 offset:63232
	ds_read_b128 v[142:145], v88 offset:63296
	ds_read_b128 v[146:149], v92 offset:128
	ds_read_b128 v[150:153], v89 offset:4608
	ds_read_b128 v[154:157], v89 offset:4672
	ds_read_b128 v[158:161], v92 offset:192
	ds_read_b128 v[162:165], v89 offset:6912
	ds_read_b128 v[166:169], v89 offset:6976
	s_waitcnt lgkmcnt(11)
	v_pk_mul_f32 v[28:29], v[28:29], v[118:119]
	v_pk_mul_f32 v[30:31], v[30:31], v[120:121]
	s_waitcnt lgkmcnt(8)
	v_pk_mul_f32 v[24:25], v[24:25], v[130:131]
	v_pk_mul_f32 v[26:27], v[26:27], v[132:133]
	s_waitcnt lgkmcnt(5)
	v_pk_mul_f32 v[16:17], v[16:17], v[146:147]
	v_pk_mul_f32 v[18:19], v[18:19], v[148:149]
	s_waitcnt lgkmcnt(2)
	v_pk_mul_f32 v[12:13], v[12:13], v[158:159]
	v_pk_mul_f32 v[14:15], v[14:15], v[160:161]
	v_mfma_f32_16x16x32_bf16 v[28:31], v[122:125], v[110:113], v[28:31]
	v_mfma_f32_16x16x32_bf16 v[24:27], v[134:137], v[110:113], v[24:27]
	v_mfma_f32_16x16x32_bf16 v[16:19], v[150:153], v[110:113], v[16:19]
	s_waitcnt lgkmcnt(1)
	v_mfma_f32_16x16x32_bf16 v[12:15], v[162:165], v[110:113], v[12:15]
	v_mfma_f32_16x16x32_bf16 v[28:31], v[126:129], v[114:117], v[28:31]
	v_mfma_f32_16x16x32_bf16 v[24:27], v[142:145], v[114:117], v[24:27]
	v_mfma_f32_16x16x32_bf16 v[16:19], v[154:157], v[114:117], v[16:19]
	s_waitcnt lgkmcnt(0)
	v_mfma_f32_16x16x32_bf16 v[12:15], v[166:169], v[114:117], v[12:15]
	ds_read_b128 v[118:121], v89 offset:9216
	ds_read_b128 v[122:125], v89 offset:9280
	ds_read_b128 v[126:129], v92 offset:256
	ds_read_b128 v[130:133], v92 offset:320
	ds_read_b128 v[134:137], v89 offset:11520
	ds_read_b128 v[142:145], v89 offset:11584
	ds_read_b128 v[146:149], v89 offset:13824
	ds_read_b128 v[150:153], v89 offset:13888
	ds_read_b128 v[154:157], v92 offset:384
	ds_read_b128 v[158:161], v92 offset:448
	ds_read_b128 v[162:165], v89 offset:16128
	ds_read_b128 v[166:169], v89 offset:16192
	s_waitcnt lgkmcnt(9)
	v_pk_mul_f32 v[20:21], v[20:21], v[126:127]
	v_pk_mul_f32 v[22:23], v[22:23], v[128:129]
	s_waitcnt lgkmcnt(8)
	v_pk_mul_f32 v[8:9], v[8:9], v[130:131]
	v_pk_mul_f32 v[10:11], v[10:11], v[132:133]
	s_waitcnt lgkmcnt(3)
	v_pk_mul_f32 v[4:5], v[4:5], v[154:155]
	v_pk_mul_f32 v[6:7], v[6:7], v[156:157]
	s_waitcnt lgkmcnt(2)
	v_pk_mul_f32 v[0:1], v[0:1], v[158:159]
	v_pk_mul_f32 v[2:3], v[2:3], v[160:161]
	v_mfma_f32_16x16x32_bf16 v[20:23], v[118:121], v[110:113], v[20:23]
	v_mfma_f32_16x16x32_bf16 v[8:11], v[134:137], v[110:113], v[8:11]
	v_mfma_f32_16x16x32_bf16 v[4:7], v[146:149], v[110:113], v[4:7]
	s_waitcnt lgkmcnt(1)
	v_mfma_f32_16x16x32_bf16 v[0:3], v[162:165], v[110:113], v[0:3]
	v_mfma_f32_16x16x32_bf16 v[20:23], v[122:125], v[114:117], v[20:23]
	v_mfma_f32_16x16x32_bf16 v[8:11], v[142:145], v[114:117], v[8:11]
	v_mfma_f32_16x16x32_bf16 v[4:7], v[150:153], v[114:117], v[4:7]
	s_waitcnt lgkmcnt(0)
	v_mfma_f32_16x16x32_bf16 v[0:3], v[166:169], v[114:117], v[0:3]
	s_add_i32 s24, s24, 64
	s_sub_i32 s10, s10, 64
	s_cmpk_eq_i32 s24, 0x400
	s_barrier
	s_cbranch_scc1 .LBB0_452
.LBB0_386:
	s_waitcnt vmcnt(31)
	v_lshlrev_b32_e32 v127, 16, v228
	v_add_f32_e32 v130, 0, v127
	s_waitcnt vmcnt(29)
	v_lshlrev_b32_e32 v128, 16, v229
	v_add_f32_e32 v129, v130, v128
	s_waitcnt vmcnt(27)
	v_lshlrev_b32_e32 v123, 16, v230
	v_add_f32_e32 v126, v129, v123
	s_waitcnt vmcnt(25)
	v_lshlrev_b32_e32 v124, 16, v231
	v_add_f32_e32 v125, v126, v124
	s_waitcnt vmcnt(23)
	v_lshlrev_b32_e32 v119, 16, v232
	v_add_f32_e32 v122, v125, v119
	s_waitcnt vmcnt(21)
	v_lshlrev_b32_e32 v120, 16, v233
	v_add_f32_e32 v121, v122, v120
	s_waitcnt vmcnt(19)
	v_lshlrev_b32_e32 v115, 16, v234
	v_add_f32_e32 v118, v121, v115
	s_waitcnt vmcnt(17)
	v_lshlrev_b32_e32 v116, 16, v235
	v_add_f32_e32 v117, v118, v116
	s_waitcnt vmcnt(15)
	v_lshlrev_b32_e32 v111, 16, v236
	v_add_f32_e32 v114, v117, v111
	s_waitcnt vmcnt(13)
	v_lshlrev_b32_e32 v112, 16, v237
	v_add_f32_e32 v113, v114, v112
	s_waitcnt vmcnt(11)
	v_lshlrev_b32_e32 v103, 16, v238
	v_add_f32_e32 v110, v113, v103
	s_waitcnt vmcnt(9)
	v_lshlrev_b32_e32 v104, 16, v239
	v_add_f32_e32 v109, v110, v104
	s_waitcnt vmcnt(7)
	v_lshlrev_b32_e32 v97, 16, v240
	v_add_f32_e32 v102, v109, v97
	s_waitcnt vmcnt(5)
	v_lshlrev_b32_e32 v99, 16, v241
	v_add_f32_e32 v101, v102, v99
	s_waitcnt vmcnt(3)
	v_lshlrev_b32_e32 v92, 16, v242
	v_add_f32_e32 v96, v101, v92
	s_waitcnt vmcnt(1)
	v_lshlrev_b32_e32 v93, 16, v243
	v_add_f32_e32 v94, v96, v93
	ds_write_b32 v83, v94
	s_waitcnt vmcnt(0)
	v_lshl_or_b32 v32, v213, 16, v212
	v_lshl_or_b32 v33, v215, 16, v214
	v_lshl_or_b32 v34, v217, 16, v216
	v_lshl_or_b32 v35, v219, 16, v218
	v_lshl_or_b32 v36, v221, 16, v220
	v_lshl_or_b32 v37, v223, 16, v222
	v_lshl_or_b32 v38, v225, 16, v224
	v_lshl_or_b32 v39, v227, 16, v226
	ds_write_b128 v45, v[32:35]
	ds_write_b128 v45, v[36:39] offset:16
	s_waitcnt lgkmcnt(0)
	s_barrier
	ds_read2st64_b32 v[34:35], v84 offset1:2
	ds_read2st64_b32 v[32:33], v84 offset0:4 offset1:6
	s_add_i32 s4, s9, s24
	s_and_b64 s[0:1], s[44:45], exec
	s_cselect_b32 s0, s4, s10
	s_ashr_i32 s1, s0, 31
	s_lshl_b64 s[0:1], s[0:1], 11
	s_add_u32 s4, s18, s0
	s_addc_u32 s5, s19, s1
	s_add_u32 s0, s20, s0
	s_addc_u32 s1, s21, s1
	global_load_ushort v228, v46, s[4:5]
	global_load_ushort v212, v46, s[0:1]
	global_load_ushort v229, v48, s[4:5]
	global_load_ushort v213, v48, s[0:1]
	global_load_ushort v230, v50, s[4:5]
	global_load_ushort v214, v50, s[0:1]
	global_load_ushort v231, v52, s[4:5]
	global_load_ushort v215, v52, s[0:1]
	global_load_ushort v232, v54, s[4:5]
	global_load_ushort v216, v54, s[0:1]
	global_load_ushort v233, v56, s[4:5]
	global_load_ushort v217, v56, s[0:1]
	global_load_ushort v234, v58, s[4:5]
	global_load_ushort v218, v58, s[0:1]
	global_load_ushort v235, v60, s[4:5]
	global_load_ushort v219, v60, s[0:1]
	global_load_ushort v236, v62, s[4:5]
	global_load_ushort v220, v62, s[0:1]
	global_load_ushort v237, v66, s[4:5]
	global_load_ushort v221, v66, s[0:1]
	global_load_ushort v238, v68, s[4:5]
	global_load_ushort v222, v68, s[0:1]
	global_load_ushort v239, v70, s[4:5]
	global_load_ushort v223, v70, s[0:1]
	global_load_ushort v240, v72, s[4:5]
	global_load_ushort v224, v72, s[0:1]
	global_load_ushort v241, v74, s[4:5]
	global_load_ushort v225, v74, s[0:1]
	global_load_ushort v242, v76, s[4:5]
	global_load_ushort v226, v76, s[0:1]
	global_load_ushort v243, v78, s[4:5]
	global_load_ushort v227, v78, s[0:1]
	s_waitcnt lgkmcnt(1)
	v_add_f32_e32 v39, v34, v35
	s_waitcnt lgkmcnt(0)
	v_add_f32_e32 v33, v32, v33
	v_add_f32_e32 v95, v39, v33
	s_and_saveexec_b64 s[0:1], s[42:43]
	s_cbranch_execz .LBB0_388
	v_mul_f32_e32 v33, 0x3fb8aa3b, v95
	v_exp_f32_e32 v33, v33
	v_add_f32_e32 v91, v91, v95
	ds_write_b32 v85, v33

.LBB0_452:
	s_waitcnt vmcnt(0)
	v_lshlrev_b32_e32 v79, 16, v228
	v_add_f32_e32 v52, 0, v79
	v_lshlrev_b32_e32 v93, 16, v229
	v_add_f32_e32 v94, v52, v93
	v_lshlrev_b32_e32 v75, 16, v230
	v_add_f32_e32 v78, v94, v75
	v_lshlrev_b32_e32 v76, 16, v231
	v_add_f32_e32 v77, v78, v76
	v_lshlrev_b32_e32 v71, 16, v232
	v_add_f32_e32 v74, v77, v71
	v_lshlrev_b32_e32 v72, 16, v233
	v_add_f32_e32 v73, v74, v72
	v_lshlrev_b32_e32 v67, 16, v234
	v_add_f32_e32 v70, v73, v67
	v_lshlrev_b32_e32 v68, 16, v235
	v_add_f32_e32 v69, v70, v68
	v_lshlrev_b32_e32 v61, 16, v236
	v_add_f32_e32 v66, v69, v61
	v_lshlrev_b32_e32 v62, 16, v237
	v_add_f32_e32 v63, v66, v62
	v_lshlrev_b32_e32 v57, 16, v238
	v_add_f32_e32 v60, v63, v57
	v_lshlrev_b32_e32 v58, 16, v239
	v_add_f32_e32 v59, v60, v58
	v_lshlrev_b32_e32 v51, 16, v240
	v_add_f32_e32 v56, v59, v51
	v_lshlrev_b32_e32 v53, 16, v241
	v_add_f32_e32 v55, v56, v53
	v_lshlrev_b32_e32 v46, 16, v242
	v_add_f32_e32 v50, v55, v46
	v_lshlrev_b32_e32 v47, 16, v243
	v_add_f32_e32 v48, v50, v47
	ds_write_b32 v83, v48
	s_waitcnt vmcnt(0)
	v_lshl_or_b32 v32, v213, 16, v212
	v_lshl_or_b32 v33, v215, 16, v214
	v_lshl_or_b32 v34, v217, 16, v216
	v_lshl_or_b32 v35, v219, 16, v218
	v_lshl_or_b32 v36, v221, 16, v220
	v_lshl_or_b32 v37, v223, 16, v222
	v_lshl_or_b32 v38, v225, 16, v224
	v_lshl_or_b32 v39, v227, 16, v226
	ds_write_b128 v45, v[32:35]
	ds_write_b128 v45, v[36:39] offset:16
	s_waitcnt lgkmcnt(0)
	s_barrier
	ds_read2st64_b32 v[34:35], v84 offset1:2
	ds_read2st64_b32 v[32:33], v84 offset0:4 offset1:6
	s_waitcnt lgkmcnt(1)
	v_add_f32_e32 v39, v34, v35
	s_waitcnt lgkmcnt(0)
	v_add_f32_e32 v33, v32, v33
	v_add_f32_e32 v49, v39, v33
	s_and_saveexec_b64 s[0:1], s[42:43]
	s_cbranch_execz .LBB0_454
	v_mul_f32_e32 v33, 0x3fb8aa3b, v49
	v_exp_f32_e32 v33, v33
	v_add_f32_e32 v91, v91, v49
	ds_write_b32 v85, v33
